# attention loops: K fragment reads issued in MFMA consumption order with counted lgkmcnt waits (6/4/2/0) instead of one full wait before the first QK MFMA
# speedup vs baseline: 1.0110x; 1.0110x over previous
; #define MFMA32(a, b, c) __builtin_amdgcn_mfma_f32_32x32x16_bf16((a), (b), (c), 0, 0, 0)
; #define NEGINF (-__builtin_inff())
; DI int crow(int i, int h) { return (i & 3) + 8 * (i >> 2) + 4 * h; }
; template <class KP, class VP, class ACT, class FILL>
; DI void attn_loop(AttnSt& st, const bf16x8 (&qf)[4], int k0, int k1, size_t vstride, KP kp, VP vp, ACT act, FILL fill) {
;     ...
;   for (int kt = k0; kt <= k1; ++kt) {
;     const int kn = (kt < k1) ? kt + 1 : k1;
;     const int kn2 = (kt + 2 <= k1) ? kt + 2 : k1;
;     {
;       const bf16_t* v0 = vp(kn);
; #pragma unroll
;       for (int j = 0; j < 8; ++j) nxt.v[j] = *(const s16x4*)(v0 + 256 * j);
;     }
;     bf16x8 k2[4];
;     {
;       const bf16_t* krow = kp(kn2);
; #pragma unroll
;       for (int ss = 0; ss < 4; ++ss) k2[ss] = *(const bf16x8*)(krow + 512 * ss);
;     }
;     f32x16 s_next;
; #pragma unroll
;     for (int i = 0; i < 16; ++i) s_next[i] = 0.f;
; #pragma unroll
;     for (int ss = 0; ss < 4; ++ss) s_next = MFMA32(nxt.k[ss], qf[ss], s_next);
;     if (act(kt)) {
;       float lg[16];
;       fill(kt, s_cur, lg);
;       softmax_step_r(st, lg, cur);
;     }
; DI void nsa_win_item(const Params& p, int b, int head, int qb, const unsigned char* blut, const float* tbl) {
;     ...
;     attn_loop(st, qf, k0, qb, 32,
;       [&](int kt) { return K + (size_t)kt * 2048 + (h * 32 + r) * 8; },
;       [&](int kt) { return Vt + (size_t)kt * 2048 + (h * 32 + r) * 4; },
;       [&](int kt) { return true; },
;       [&](int kt, const f32x16& s, float (&lg)[16]) {
;         int dist[16]; float bv[16];
; #pragma unroll
;         for (int i = 0; i < 16; ++i) dist[i] = t - (kt * 32 + crow(i, h));
;         bias16(blut, tblh, dist, bv);
; #pragma unroll
;         for (int i = 0; i < 16; ++i) lg[i] = (dist[i] >= 0 && dist[i] < 512) ? s[i] + bv[i] : NEGINF;
;       });
.Lawin6_loop:
	s_waitcnt vmcnt(2)
	s_barrier
	s_lshr_b32 s23, s56, 1
	s_add_u32 s23, s23, 2
	s_sub_u32 s61, s64, 0x4000
	s_cmp_lt_u32 s61, 0x10000
	s_cselect_b32 s61, 0x18000, s61
	s_lshr_b32 s24, s59, 1
	s_min_u32 s24, s23, s24
	s_lshl_b32 s26, s24, 13
	s_lshl_b32 s24, s58, 10
	s_add_u32 s26, s26, s24
	s_mov_b32 s27, 0
	v_lshl_add_u64 v[248:249], v[116:117], 0, s[26:27]
	v_lshl_add_u64 v[250:251], v[114:115], 0, s[26:27]
	v_add_co_u32_e32 v250, vcc, v250, v247
	v_addc_co_u32_e32 v251, vcc, 0, v251, vcc
	s_add_u32 s24, s24, s61
	s_mov_b32 m0, s24
	s_nop 0
	global_load_lds_dwordx4 v[248:249], off
	s_add_u32 s24, s24, 0x2000
	s_mov_b32 m0, s24
	s_nop 0
	global_load_lds_dwordx4 v[250:251], off
	s_cmp_le_u32 s56, s60
	s_cbranch_scc0 .Lawin6_skip
	s_add_u32 s24, s56, 1
	s_cmp_ge_u32 s24, s65
	s_cbranch_scc0 .Lawin6_skip
	v_lshl_add_u32 v248, v247, 1, s64
	ds_read_b128 v[80:83], v248 offset:0
	ds_read_b128 v[96:99], v248 offset:4096
	ds_read_b128 v[84:87], v248 offset:1024
	ds_read_b128 v[100:103], v248 offset:5120
	ds_read_b128 v[88:91], v248 offset:2048
	ds_read_b128 v[104:107], v248 offset:6144
	ds_read_b128 v[92:95], v248 offset:3072
	ds_read_b128 v[108:111], v248 offset:7168
	s_sub_i32 s61, s60, s56
	s_waitcnt lgkmcnt(6)
	v_mfma_f32_32x32x16_bf16 v[32:47], v[80:83], v[64:67], 0
	v_mfma_f32_32x32x16_bf16 v[48:63], v[96:99], v[64:67], 0
	s_waitcnt lgkmcnt(4)
	v_mfma_f32_32x32x16_bf16 v[32:47], v[84:87], v[68:71], v[32:47]
	v_mfma_f32_32x32x16_bf16 v[48:63], v[100:103], v[68:71], v[48:63]
	s_waitcnt lgkmcnt(2)
	v_mfma_f32_32x32x16_bf16 v[32:47], v[88:91], v[72:75], v[32:47]
	v_mfma_f32_32x32x16_bf16 v[48:63], v[104:107], v[72:75], v[48:63]
	s_waitcnt lgkmcnt(0)
	v_mfma_f32_32x32x16_bf16 v[32:47], v[92:95], v[76:79], v[32:47]
	v_mfma_f32_32x32x16_bf16 v[48:63], v[108:111], v[76:79], v[48:63]
	v_add_u32_e32 v250, s64, v247
	ds_read_b64 v[146:147], v250 offset:8192
	ds_read_b64 v[148:149], v250 offset:8704
	ds_read_b64 v[150:151], v250 offset:9216
	ds_read_b64 v[152:153], v250 offset:9728
	ds_read_b64 v[154:155], v250 offset:10240
	ds_read_b64 v[156:157], v250 offset:10752
	ds_read_b64 v[158:159], v250 offset:11264
	ds_read_b64 v[160:161], v250 offset:11776
	ds_read_b64 v[162:163], v250 offset:12288
	ds_read_b64 v[164:165], v250 offset:12800
	ds_read_b64 v[166:167], v250 offset:13312
	ds_read_b64 v[168:169], v250 offset:13824
	ds_read_b64 v[170:171], v250 offset:14336
	ds_read_b64 v[172:173], v250 offset:14848
	ds_read_b64 v[174:175], v250 offset:15360
	ds_read_b64 v[176:177], v250 offset:15872
	s_cmp_ge_i32 s61, 50
	s_cbranch_scc1 .Lawin6_far
	s_lshl_b32 s23, s61, 5
	v_add_u32_e32 v241, s23, v222
	v_lshl_add_u32 v244, v241, 2, v242
	v_subrev_u32_e32 v245, 128, v244
	ds_read_b32 v224, v244 offset:108
	ds_read_b32 v225, v244 offset:104
	ds_read_b32 v226, v244 offset:100
	ds_read_b32 v227, v244 offset:96
	ds_read_b32 v228, v244 offset:76
	ds_read_b32 v229, v244 offset:72
	ds_read_b32 v230, v244 offset:68
	ds_read_b32 v231, v244 offset:64
	ds_read_b32 v232, v244 offset:44
	ds_read_b32 v233, v244 offset:40
	ds_read_b32 v234, v244 offset:36
	ds_read_b32 v235, v244 offset:32
	ds_read_b32 v236, v244 offset:12
	ds_read_b32 v237, v244 offset:8
	ds_read_b32 v238, v244 offset:4
	ds_read_b32 v239, v244 offset:0
	s_waitcnt lgkmcnt(8)
	v_add_f32_e32 v32, v32, v224
	v_add_f32_e32 v33, v33, v225
	v_add_f32_e32 v34, v34, v226
	v_add_f32_e32 v35, v35, v227
	v_add_f32_e32 v36, v36, v228
	v_add_f32_e32 v37, v37, v229
	v_add_f32_e32 v38, v38, v230
	v_add_f32_e32 v39, v39, v231
	s_waitcnt lgkmcnt(0)
	v_add_f32_e32 v40, v40, v232
	v_add_f32_e32 v41, v41, v233
	v_add_f32_e32 v42, v42, v234
	v_add_f32_e32 v43, v43, v235
	v_add_f32_e32 v44, v44, v236
	v_add_f32_e32 v45, v45, v237
	v_add_f32_e32 v46, v46, v238
	v_add_f32_e32 v47, v47, v239
	ds_read_b32 v224, v245 offset:108
	ds_read_b32 v225, v245 offset:104
	ds_read_b32 v226, v245 offset:100
	ds_read_b32 v227, v245 offset:96
	ds_read_b32 v228, v245 offset:76
	ds_read_b32 v229, v245 offset:72
	ds_read_b32 v230, v245 offset:68
	ds_read_b32 v231, v245 offset:64
	ds_read_b32 v232, v245 offset:44
	ds_read_b32 v233, v245 offset:40
	ds_read_b32 v234, v245 offset:36
	ds_read_b32 v235, v245 offset:32
	ds_read_b32 v236, v245 offset:12
	ds_read_b32 v237, v245 offset:8
	ds_read_b32 v238, v245 offset:4
	ds_read_b32 v239, v245 offset:0
	s_waitcnt lgkmcnt(8)
	v_add_f32_e32 v48, v48, v224
	v_add_f32_e32 v49, v49, v225
	v_add_f32_e32 v50, v50, v226
	v_add_f32_e32 v51, v51, v227
	v_add_f32_e32 v52, v52, v228
	v_add_f32_e32 v53, v53, v229
	v_add_f32_e32 v54, v54, v230
	v_add_f32_e32 v55, v55, v231
	s_waitcnt lgkmcnt(0)
	v_add_f32_e32 v56, v56, v232
	v_add_f32_e32 v57, v57, v233
	v_add_f32_e32 v58, v58, v234
	v_add_f32_e32 v59, v59, v235
	v_add_f32_e32 v60, v60, v236
	v_add_f32_e32 v61, v61, v237
	v_add_f32_e32 v62, v62, v238
	v_add_f32_e32 v63, v63, v239
	s_cmp_ge_i32 s61, 15
	s_cbranch_scc0 .Lawin6_nowin
; #define NEGINF (-__builtin_inff())
; DI int crow(int i, int h) { return (i & 3) + 8 * (i >> 2) + 4 * h; }
; DI void nsa_win_item(const Params& p, int b, int head, int qb, const unsigned char* blut, const float* tbl) {
;     ...
;       [&](int kt, const f32x16& s, float (&lg)[16]) {
;         int dist[16]; float bv[16];
; #pragma unroll
;         for (int i = 0; i < 16; ++i) dist[i] = t - (kt * 32 + crow(i, h));
;         bias16(blut, tblh, dist, bv);
; #pragma unroll
;         for (int i = 0; i < 16; ++i) lg[i] = (dist[i] >= 0 && dist[i] < 512) ? s[i] + bv[i] : NEGINF;
;       });
	v_subrev_u32_e32 v246, 32, v241
	v_cmp_gt_i32_e32 vcc, 0x200, v241
	s_nop 1
	v_cndmask_b32_e32 v32, v199, v32, vcc
	v_cmp_gt_i32_e32 vcc, 0x201, v241
	s_nop 1
	v_cndmask_b32_e32 v33, v199, v33, vcc
	v_cmp_gt_i32_e32 vcc, 0x202, v241
	s_nop 1
	v_cndmask_b32_e32 v34, v199, v34, vcc
	v_cmp_gt_i32_e32 vcc, 0x203, v241
	s_nop 1
	v_cndmask_b32_e32 v35, v199, v35, vcc
	v_cmp_gt_i32_e32 vcc, 0x208, v241
	s_nop 1
	v_cndmask_b32_e32 v36, v199, v36, vcc
	v_cmp_gt_i32_e32 vcc, 0x209, v241
	s_nop 1
	v_cndmask_b32_e32 v37, v199, v37, vcc
	v_cmp_gt_i32_e32 vcc, 0x20a, v241
	s_nop 1
	v_cndmask_b32_e32 v38, v199, v38, vcc
	v_cmp_gt_i32_e32 vcc, 0x20b, v241
	s_nop 1
	v_cndmask_b32_e32 v39, v199, v39, vcc
	v_cmp_gt_i32_e32 vcc, 0x210, v241
	s_nop 1
	v_cndmask_b32_e32 v40, v199, v40, vcc
	v_cmp_gt_i32_e32 vcc, 0x211, v241
	s_nop 1
	v_cndmask_b32_e32 v41, v199, v41, vcc
	v_cmp_gt_i32_e32 vcc, 0x212, v241
	s_nop 1
	v_cndmask_b32_e32 v42, v199, v42, vcc
	v_cmp_gt_i32_e32 vcc, 0x213, v241
	s_nop 1
	v_cndmask_b32_e32 v43, v199, v43, vcc
	v_cmp_gt_i32_e32 vcc, 0x218, v241
	s_nop 1
	v_cndmask_b32_e32 v44, v199, v44, vcc
	v_cmp_gt_i32_e32 vcc, 0x219, v241
	s_nop 1
	v_cndmask_b32_e32 v45, v199, v45, vcc
	v_cmp_gt_i32_e32 vcc, 0x21a, v241
	s_nop 1
	v_cndmask_b32_e32 v46, v199, v46, vcc
	v_cmp_gt_i32_e32 vcc, 0x21b, v241
	s_nop 1
	v_cndmask_b32_e32 v47, v199, v47, vcc
	v_cmp_gt_i32_e32 vcc, 0x200, v246
	s_nop 1
	v_cndmask_b32_e32 v48, v199, v48, vcc
	v_cmp_gt_i32_e32 vcc, 0x201, v246
	s_nop 1
	v_cndmask_b32_e32 v49, v199, v49, vcc
	v_cmp_gt_i32_e32 vcc, 0x202, v246
	s_nop 1
	v_cndmask_b32_e32 v50, v199, v50, vcc
	v_cmp_gt_i32_e32 vcc, 0x203, v246
	s_nop 1
	v_cndmask_b32_e32 v51, v199, v51, vcc
	v_cmp_gt_i32_e32 vcc, 0x208, v246
	s_nop 1
	v_cndmask_b32_e32 v52, v199, v52, vcc
	v_cmp_gt_i32_e32 vcc, 0x209, v246
	s_nop 1
	v_cndmask_b32_e32 v53, v199, v53, vcc
	v_cmp_gt_i32_e32 vcc, 0x20a, v246
	s_nop 1
	v_cndmask_b32_e32 v54, v199, v54, vcc
	v_cmp_gt_i32_e32 vcc, 0x20b, v246
	s_nop 1
	v_cndmask_b32_e32 v55, v199, v55, vcc
	v_cmp_gt_i32_e32 vcc, 0x210, v246
	s_nop 1
	v_cndmask_b32_e32 v56, v199, v56, vcc
	v_cmp_gt_i32_e32 vcc, 0x211, v246
	s_nop 1
	v_cndmask_b32_e32 v57, v199, v57, vcc
	v_cmp_gt_i32_e32 vcc, 0x212, v246
	s_nop 1
	v_cndmask_b32_e32 v58, v199, v58, vcc
	v_cmp_gt_i32_e32 vcc, 0x213, v246
	s_nop 1
	v_cndmask_b32_e32 v59, v199, v59, vcc
	v_cmp_gt_i32_e32 vcc, 0x218, v246
	s_nop 1
	v_cndmask_b32_e32 v60, v199, v60, vcc
	v_cmp_gt_i32_e32 vcc, 0x219, v246
	s_nop 1
	v_cndmask_b32_e32 v61, v199, v61, vcc
	v_cmp_gt_i32_e32 vcc, 0x21a, v246
	s_nop 1
	v_cndmask_b32_e32 v62, v199, v62, vcc
	v_cmp_gt_i32_e32 vcc, 0x21b, v246
	s_nop 1
	v_cndmask_b32_e32 v63, v199, v63, vcc

; #define MFMA32(a, b, c) __builtin_amdgcn_mfma_f32_32x32x16_bf16((a), (b), (c), 0, 0, 0)
; template <class KP, class VP, class ACT, class FILL>
; DI void attn_loop(AttnSt& st, const bf16x8 (&qf)[4], int k0, int k1, size_t vstride, KP kp, VP vp, ACT act, FILL fill) {
;     ...
;   for (int kt = k0; kt <= k1; ++kt) {
;     const int kn = (kt < k1) ? kt + 1 : k1;
;     const int kn2 = (kt + 2 <= k1) ? kt + 2 : k1;
;     {
;       const bf16_t* v0 = vp(kn);
; #pragma unroll
;       for (int j = 0; j < 8; ++j) nxt.v[j] = *(const s16x4*)(v0 + 256 * j);
;     }
;     bf16x8 k2[4];
;     {
;       const bf16_t* krow = kp(kn2);
; #pragma unroll
;       for (int ss = 0; ss < 4; ++ss) k2[ss] = *(const bf16x8*)(krow + 512 * ss);
;     }
;     f32x16 s_next;
; #pragma unroll
;     for (int i = 0; i < 16; ++i) s_next[i] = 0.f;
; #pragma unroll
;     for (int ss = 0; ss < 4; ++ss) s_next = MFMA32(nxt.k[ss], qf[ss], s_next);
; DI void nsa_main_item(const Params& p, int b, int head, int qb, const unsigned char* blut, const float* tbl) {
;     ...
;     attn_loop(st, qf, 0, qb, 32,
;       [&](int kt) { return K + (size_t)kt * 2048 + (h * 32 + r) * 8; },
;       [&](int kt) { return Vt + (size_t)kt * 2048 + (h * 32 + r) * 4; },
;       [&](int kt) { return __ballot((selm >> (kt >> 1)) & 1ull) != 0ull; },
;       [&](int kt, const f32x16& s, float (&lg)[16]) {
;         const bool bs = (selm >> (kt >> 1)) & 1ull;
.Lasel_loop:
	s_waitcnt vmcnt(2)
	s_barrier
	s_lshr_b32 s23, s56, 1
	s_add_u32 s23, s23, 2
	s_sub_u32 s61, s100, 0x4000
	s_cmp_lt_u32 s61, 0x10000
	s_cselect_b32 s61, 0x18000, s61
	s_lshr_b32 s24, s59, 1
	s_min_u32 s24, s23, s24
	s_lshl_b32 s26, s24, 13
	s_lshl_b32 s24, s58, 10
	s_add_u32 s26, s26, s24
	s_mov_b32 s27, 0
	v_lshl_add_u64 v[248:249], v[148:149], 0, s[26:27]
	v_lshl_add_u64 v[250:251], v[170:171], 0, s[26:27]
	v_add_co_u32_e32 v250, vcc, v250, v247
	v_addc_co_u32_e32 v251, vcc, 0, v251, vcc
	s_add_u32 s24, s24, s61
	s_mov_b32 m0, s24
	s_nop 0
	global_load_lds_dwordx4 v[248:249], off
	s_add_u32 s24, s24, 0x2000
	s_mov_b32 m0, s24
	s_nop 0
	global_load_lds_dwordx4 v[250:251], off
	s_cmp_le_u32 s56, s60
	s_cbranch_scc0 .Lasel_skip
	v_lshl_add_u32 v248, v247, 1, s100
	ds_read_b128 v[96:99], v248 offset:0
	ds_read_b128 v[112:115], v248 offset:4096
	ds_read_b128 v[100:103], v248 offset:1024
	ds_read_b128 v[116:119], v248 offset:5120
	ds_read_b128 v[104:107], v248 offset:2048
	ds_read_b128 v[120:123], v248 offset:6144
	ds_read_b128 v[108:111], v248 offset:3072
	ds_read_b128 v[124:127], v248 offset:7168
	s_sub_i32 s61, s60, s56
	s_lshr_b32 s23, s56, 1
	v_lshrrev_b64 v[248:249], s23, v[168:169]
	v_and_b32_e32 v248, 1, v248
	v_cmp_eq_u32_e64 s[62:63], 1, v248
	s_waitcnt lgkmcnt(6)
	v_mfma_f32_32x32x16_bf16 v[32:47], v[96:99], v[80:83], 0
	v_mfma_f32_32x32x16_bf16 v[48:63], v[112:115], v[80:83], 0
	s_waitcnt lgkmcnt(4)
	v_mfma_f32_32x32x16_bf16 v[32:47], v[100:103], v[84:87], v[32:47]
	v_mfma_f32_32x32x16_bf16 v[48:63], v[116:119], v[84:87], v[48:63]
	s_waitcnt lgkmcnt(2)
	v_mfma_f32_32x32x16_bf16 v[32:47], v[104:107], v[88:91], v[32:47]
	v_mfma_f32_32x32x16_bf16 v[48:63], v[120:123], v[88:91], v[48:63]
	s_waitcnt lgkmcnt(0)
	v_mfma_f32_32x32x16_bf16 v[32:47], v[108:111], v[92:95], v[32:47]
	v_mfma_f32_32x32x16_bf16 v[48:63], v[124:127], v[92:95], v[48:63]
	v_add_u32_e32 v250, s100, v247
	ds_read_b64 v[64:65], v250 offset:8192
	ds_read_b64 v[66:67], v250 offset:8704
	ds_read_b64 v[68:69], v250 offset:9216
	ds_read_b64 v[70:71], v250 offset:9728
	ds_read_b64 v[72:73], v250 offset:10240
	ds_read_b64 v[74:75], v250 offset:10752
	ds_read_b64 v[76:77], v250 offset:11264
	ds_read_b64 v[78:79], v250 offset:11776
	ds_read_b64 v[172:173], v250 offset:12288
	ds_read_b64 v[174:175], v250 offset:12800
	ds_read_b64 v[176:177], v250 offset:13312
	ds_read_b64 v[178:179], v250 offset:13824
	ds_read_b64 v[180:181], v250 offset:14336
	ds_read_b64 v[182:183], v250 offset:14848
	ds_read_b64 v[184:185], v250 offset:15360
	ds_read_b64 v[186:187], v250 offset:15872
	s_cmp_ge_i32 s61, 50
	s_cbranch_scc1 .Lasel_far
; #define NEGINF (-__builtin_inff())
; DI int crow(int i, int h) { return (i & 3) + 8 * (i >> 2) + 4 * h; }
; DI void nsa_main_item(const Params& p, int b, int head, int qb, const unsigned char* blut, const float* tbl) {
;     ...
;           int dist[16]; float bv[16];
; #pragma unroll
;           for (int i = 0; i < 16; ++i) dist[i] = t - (kt * 32 + crow(i, h));
;           bias16(blut, tblh, dist, bv);
; #pragma unroll
;           for (int i = 0; i < 16; ++i) lg[i] = (bs && dist[i] >= 0) ? s[i] + bv[i] : NEGINF;
	s_lshl_b32 s23, s61, 5
	v_add_u32_e32 v241, s23, v221
	v_lshl_add_u32 v244, v241, 2, v242
	v_subrev_u32_e32 v245, 128, v244
	ds_read_b32 v224, v244 offset:108
	ds_read_b32 v225, v244 offset:104
	ds_read_b32 v226, v244 offset:100
	ds_read_b32 v227, v244 offset:96
	ds_read_b32 v228, v244 offset:76
	ds_read_b32 v229, v244 offset:72
	ds_read_b32 v230, v244 offset:68
	ds_read_b32 v231, v244 offset:64
	ds_read_b32 v232, v244 offset:44
	ds_read_b32 v233, v244 offset:40
	ds_read_b32 v234, v244 offset:36
	ds_read_b32 v235, v244 offset:32
	ds_read_b32 v236, v244 offset:12
	ds_read_b32 v237, v244 offset:8
	ds_read_b32 v238, v244 offset:4
	ds_read_b32 v239, v244 offset:0
	s_waitcnt lgkmcnt(8)
	v_add_f32_e32 v32, v32, v224
	v_add_f32_e32 v33, v33, v225
	v_add_f32_e32 v34, v34, v226
	v_add_f32_e32 v35, v35, v227
	v_add_f32_e32 v36, v36, v228
	v_add_f32_e32 v37, v37, v229
	v_add_f32_e32 v38, v38, v230
	v_add_f32_e32 v39, v39, v231
	s_waitcnt lgkmcnt(0)
	v_add_f32_e32 v40, v40, v232
	v_add_f32_e32 v41, v41, v233
	v_add_f32_e32 v42, v42, v234
	v_add_f32_e32 v43, v43, v235
	v_add_f32_e32 v44, v44, v236
	v_add_f32_e32 v45, v45, v237
	v_add_f32_e32 v46, v46, v238
	v_add_f32_e32 v47, v47, v239
	ds_read_b32 v224, v245 offset:108
	ds_read_b32 v225, v245 offset:104
	ds_read_b32 v226, v245 offset:100
	ds_read_b32 v227, v245 offset:96
	ds_read_b32 v228, v245 offset:76
	ds_read_b32 v229, v245 offset:72
	ds_read_b32 v230, v245 offset:68
	ds_read_b32 v231, v245 offset:64
	ds_read_b32 v232, v245 offset:44
	ds_read_b32 v233, v245 offset:40
	ds_read_b32 v234, v245 offset:36
	ds_read_b32 v235, v245 offset:32
	ds_read_b32 v236, v245 offset:12
	ds_read_b32 v237, v245 offset:8
	ds_read_b32 v238, v245 offset:4
	ds_read_b32 v239, v245 offset:0
	s_waitcnt lgkmcnt(8)
	v_add_f32_e32 v48, v48, v224
	v_add_f32_e32 v49, v49, v225
	v_add_f32_e32 v50, v50, v226
	v_add_f32_e32 v51, v51, v227
	v_add_f32_e32 v52, v52, v228
	v_add_f32_e32 v53, v53, v229
	v_add_f32_e32 v54, v54, v230
	v_add_f32_e32 v55, v55, v231
	s_waitcnt lgkmcnt(0)
	v_add_f32_e32 v56, v56, v232
	v_add_f32_e32 v57, v57, v233
	v_add_f32_e32 v58, v58, v234
	v_add_f32_e32 v59, v59, v235
	v_add_f32_e32 v60, v60, v236
	v_add_f32_e32 v61, v61, v237
	v_add_f32_e32 v62, v62, v238
	v_add_f32_e32 v63, v63, v239
	s_cmp_ge_i32 s61, 2
	s_cbranch_scc1 .Lasel_softmax
	v_subrev_u32_e32 v246, 32, v241
	v_cmp_le_i32_e32 vcc, 0, v241
	s_nop 1
	v_cndmask_b32_e32 v32, v199, v32, vcc
	v_cmp_le_i32_e32 vcc, 1, v241
	s_nop 1
	v_cndmask_b32_e32 v33, v199, v33, vcc
	v_cmp_le_i32_e32 vcc, 2, v241
	s_nop 1
	v_cndmask_b32_e32 v34, v199, v34, vcc
	v_cmp_le_i32_e32 vcc, 3, v241
	s_nop 1
	v_cndmask_b32_e32 v35, v199, v35, vcc
	v_cmp_le_i32_e32 vcc, 8, v241
	s_nop 1
	v_cndmask_b32_e32 v36, v199, v36, vcc
	v_cmp_le_i32_e32 vcc, 9, v241
	s_nop 1
	v_cndmask_b32_e32 v37, v199, v37, vcc
	v_cmp_le_i32_e32 vcc, 10, v241
	s_nop 1
	v_cndmask_b32_e32 v38, v199, v38, vcc
	v_cmp_le_i32_e32 vcc, 11, v241
	s_nop 1
	v_cndmask_b32_e32 v39, v199, v39, vcc
	v_cmp_le_i32_e32 vcc, 16, v241
	s_nop 1
	v_cndmask_b32_e32 v40, v199, v40, vcc
	v_cmp_le_i32_e32 vcc, 17, v241
	s_nop 1
	v_cndmask_b32_e32 v41, v199, v41, vcc
	v_cmp_le_i32_e32 vcc, 18, v241
	s_nop 1
	v_cndmask_b32_e32 v42, v199, v42, vcc
	v_cmp_le_i32_e32 vcc, 19, v241
	s_nop 1
	v_cndmask_b32_e32 v43, v199, v43, vcc
	v_cmp_le_i32_e32 vcc, 24, v241
	s_nop 1
	v_cndmask_b32_e32 v44, v199, v44, vcc
	v_cmp_le_i32_e32 vcc, 25, v241
	s_nop 1
	v_cndmask_b32_e32 v45, v199, v45, vcc
	v_cmp_le_i32_e32 vcc, 26, v241
	s_nop 1
	v_cndmask_b32_e32 v46, v199, v46, vcc
	v_cmp_le_i32_e32 vcc, 27, v241
	s_nop 1
	v_cndmask_b32_e32 v47, v199, v47, vcc
	v_cmp_le_i32_e32 vcc, 0, v246
	s_nop 1
	v_cndmask_b32_e32 v48, v199, v48, vcc
	v_cmp_le_i32_e32 vcc, 1, v246
	s_nop 1
	v_cndmask_b32_e32 v49, v199, v49, vcc
	v_cmp_le_i32_e32 vcc, 2, v246
	s_nop 1
	v_cndmask_b32_e32 v50, v199, v50, vcc
	v_cmp_le_i32_e32 vcc, 3, v246
	s_nop 1
	v_cndmask_b32_e32 v51, v199, v51, vcc
	v_cmp_le_i32_e32 vcc, 8, v246
	s_nop 1
	v_cndmask_b32_e32 v52, v199, v52, vcc
	v_cmp_le_i32_e32 vcc, 9, v246
	s_nop 1
	v_cndmask_b32_e32 v53, v199, v53, vcc
	v_cmp_le_i32_e32 vcc, 10, v246
	s_nop 1
	v_cndmask_b32_e32 v54, v199, v54, vcc
	v_cmp_le_i32_e32 vcc, 11, v246
	s_nop 1
	v_cndmask_b32_e32 v55, v199, v55, vcc
	v_cmp_le_i32_e32 vcc, 16, v246
	s_nop 1
	v_cndmask_b32_e32 v56, v199, v56, vcc
	v_cmp_le_i32_e32 vcc, 17, v246
	s_nop 1
	v_cndmask_b32_e32 v57, v199, v57, vcc
	v_cmp_le_i32_e32 vcc, 18, v246
	s_nop 1
	v_cndmask_b32_e32 v58, v199, v58, vcc
	v_cmp_le_i32_e32 vcc, 19, v246
	s_nop 1
	v_cndmask_b32_e32 v59, v199, v59, vcc
	v_cmp_le_i32_e32 vcc, 24, v246
	s_nop 1
	v_cndmask_b32_e32 v60, v199, v60, vcc
	v_cmp_le_i32_e32 vcc, 25, v246
	s_nop 1
	v_cndmask_b32_e32 v61, v199, v61, vcc
	v_cmp_le_i32_e32 vcc, 26, v246
	s_nop 1
	v_cndmask_b32_e32 v62, v199, v62, vcc
	v_cmp_le_i32_e32 vcc, 27, v246
	s_nop 1
	v_cndmask_b32_e32 v63, v199, v63, vcc
	s_branch .Lasel_softmax

; #define MFMA32(a, b, c) __builtin_amdgcn_mfma_f32_32x32x16_bf16((a), (b), (c), 0, 0, 0)
; #define NEGINF (-__builtin_inff())
; DI int crow(int i, int h) { return (i & 3) + 8 * (i >> 2) + 4 * h; }
; template <class KP, class VP, class ACT, class FILL>
; DI void attn_loop(AttnSt& st, const bf16x8 (&qf)[4], int k0, int k1, size_t vstride, KP kp, VP vp, ACT act, FILL fill) {
;     ...
;   for (int kt = k0; kt <= k1; ++kt) {
;     const int kn = (kt < k1) ? kt + 1 : k1;
;     const int kn2 = (kt + 2 <= k1) ? kt + 2 : k1;
;     {
;       const bf16_t* v0 = vp(kn);
; #pragma unroll
;       for (int j = 0; j < 8; ++j) nxt.v[j] = *(const s16x4*)(v0 + 256 * j);
;     }
;     bf16x8 k2[4];
;     {
;       const bf16_t* krow = kp(kn2);
; #pragma unroll
;       for (int ss = 0; ss < 4; ++ss) k2[ss] = *(const bf16x8*)(krow + 512 * ss);
;     }
;     f32x16 s_next;
; #pragma unroll
;     for (int i = 0; i < 16; ++i) s_next[i] = 0.f;
; #pragma unroll
;     for (int ss = 0; ss < 4; ++ss) s_next = MFMA32(nxt.k[ss], qf[ss], s_next);
; DI void moba_item(const Params& p, int b, int hd, int qb, const unsigned char* blut, const float* tbl) {
;     ...
;   attn_loop(st, qf, 0, qb, 32,
;     [&](int kt) { return K + (size_t)kt * 2048 + (h * 32 + r) * 8; },
;     [&](int kt) { return Vt + (size_t)kt * 2048 + (h * 32 + r) * 4; },
;     [&](int kt) { return __ballot((mmask >> (kt >> 3)) & 1u) != 0ull; },
;     [&](int kt, const f32x16& s, float (&lg)[16]) {
;       const bool bs = (mmask >> (kt >> 3)) & 1u;
;       if (qb * 32 - (kt * 32 + 31) >= 1513) {
;         const float b31 = tblh[31];
; #pragma unroll
;         for (int i = 0; i < 16; ++i) lg[i] = bs ? s[i] + b31 : NEGINF;
;       } else {
;         int dist[16]; float bv[16];
; #pragma unroll
;         for (int i = 0; i < 16; ++i) dist[i] = t - (kt * 32 + crow(i, h));
;         bias16(blut, tblh, dist, bv);
; #pragma unroll
;         for (int i = 0; i < 16; ++i) lg[i] = (bs && dist[i] >= 0) ? s[i] + bv[i] : NEGINF;
;       }
;     });
.Lamoba_loop:
	s_waitcnt vmcnt(2)
	s_barrier
	s_lshr_b32 s23, s56, 1
	s_add_u32 s23, s23, 2
	s_sub_u32 s61, s100, 0x4000
	s_cmp_lt_u32 s61, 0x10000
	s_cselect_b32 s61, 0x18000, s61
	s_lshr_b32 s24, s59, 1
	s_min_u32 s24, s23, s24
	s_lshl_b32 s26, s24, 13
	s_lshl_b32 s24, s58, 10
	s_add_u32 s26, s26, s24
	s_mov_b32 s27, 0
	v_lshl_add_u64 v[186:187], v[134:135], 0, s[26:27]
	v_lshl_add_u64 v[218:219], v[136:137], 0, s[26:27]
	v_add_co_u32_e32 v218, vcc, v218, v185
	v_addc_co_u32_e32 v219, vcc, 0, v219, vcc
	s_add_u32 s24, s24, s61
	s_mov_b32 m0, s24
	s_nop 0
	global_load_lds_dwordx4 v[186:187], off
	s_add_u32 s24, s24, 0x2000
	s_mov_b32 m0, s24
	s_nop 0
	global_load_lds_dwordx4 v[218:219], off
	s_cmp_le_u32 s56, s60
	s_cbranch_scc0 .Lamoba_skip
	v_lshl_add_u32 v186, v185, 1, s100
	ds_read_b128 v[96:99], v186 offset:0
	ds_read_b128 v[112:115], v186 offset:4096
	ds_read_b128 v[100:103], v186 offset:1024
	ds_read_b128 v[116:119], v186 offset:5120
	ds_read_b128 v[104:107], v186 offset:2048
	ds_read_b128 v[120:123], v186 offset:6144
	ds_read_b128 v[108:111], v186 offset:3072
	ds_read_b128 v[124:127], v186 offset:7168
	s_sub_i32 s61, s60, s56
	s_lshr_b32 s23, s56, 3
	v_bfe_u32 v184, v157, s23, 1
	v_cmp_eq_u32_e64 s[62:63], 1, v184
	s_waitcnt lgkmcnt(6)
	v_mfma_f32_32x32x16_bf16 v[32:47], v[96:99], v[80:83], 0
	v_mfma_f32_32x32x16_bf16 v[48:63], v[112:115], v[80:83], 0
	s_waitcnt lgkmcnt(4)
	v_mfma_f32_32x32x16_bf16 v[32:47], v[100:103], v[84:87], v[32:47]
	v_mfma_f32_32x32x16_bf16 v[48:63], v[116:119], v[84:87], v[48:63]
	s_waitcnt lgkmcnt(2)
	v_mfma_f32_32x32x16_bf16 v[32:47], v[104:107], v[88:91], v[32:47]
	v_mfma_f32_32x32x16_bf16 v[48:63], v[120:123], v[88:91], v[48:63]
	s_waitcnt lgkmcnt(0)
	v_mfma_f32_32x32x16_bf16 v[32:47], v[108:111], v[92:95], v[32:47]
	v_mfma_f32_32x32x16_bf16 v[48:63], v[124:127], v[92:95], v[48:63]
	v_add_u32_e32 v218, s100, v185
	ds_read_b64 v[64:65], v218 offset:8192
	ds_read_b64 v[66:67], v218 offset:8704
	ds_read_b64 v[68:69], v218 offset:9216
	ds_read_b64 v[70:71], v218 offset:9728
	ds_read_b64 v[72:73], v218 offset:10240
	ds_read_b64 v[74:75], v218 offset:10752
	ds_read_b64 v[76:77], v218 offset:11264
	ds_read_b64 v[78:79], v218 offset:11776
	ds_read_b64 v[138:139], v218 offset:12288
	ds_read_b64 v[140:141], v218 offset:12800
	ds_read_b64 v[142:143], v218 offset:13312
	ds_read_b64 v[144:145], v218 offset:13824
	ds_read_b64 v[146:147], v218 offset:14336
	ds_read_b64 v[148:149], v218 offset:14848
	ds_read_b64 v[150:151], v218 offset:15360
	ds_read_b64 v[152:153], v218 offset:15872
	s_cmp_ge_i32 s61, 50
	s_cbranch_scc1 .Lamoba_far
	s_lshl_b32 s23, s61, 5
	v_add_u32_e32 v179, s23, v158
	v_lshl_add_u32 v182, v179, 2, v180
	v_subrev_u32_e32 v183, 128, v182
	ds_read_b32 v162, v182 offset:108
	ds_read_b32 v163, v182 offset:104
	ds_read_b32 v164, v182 offset:100
	ds_read_b32 v165, v182 offset:96
	ds_read_b32 v166, v182 offset:76
	ds_read_b32 v167, v182 offset:72
	ds_read_b32 v168, v182 offset:68
	ds_read_b32 v169, v182 offset:64
	ds_read_b32 v170, v182 offset:44
	ds_read_b32 v171, v182 offset:40
	ds_read_b32 v172, v182 offset:36
	ds_read_b32 v173, v182 offset:32
	ds_read_b32 v174, v182 offset:12
	ds_read_b32 v175, v182 offset:8
	ds_read_b32 v176, v182 offset:4
	ds_read_b32 v177, v182 offset:0
	s_waitcnt lgkmcnt(8)
	v_add_f32_e32 v32, v32, v162
	v_add_f32_e32 v33, v33, v163
	v_add_f32_e32 v34, v34, v164
	v_add_f32_e32 v35, v35, v165
	v_add_f32_e32 v36, v36, v166
	v_add_f32_e32 v37, v37, v167
	v_add_f32_e32 v38, v38, v168
	v_add_f32_e32 v39, v39, v169
	s_waitcnt lgkmcnt(0)
	v_add_f32_e32 v40, v40, v170
	v_add_f32_e32 v41, v41, v171
	v_add_f32_e32 v42, v42, v172
	v_add_f32_e32 v43, v43, v173
	v_add_f32_e32 v44, v44, v174
	v_add_f32_e32 v45, v45, v175
	v_add_f32_e32 v46, v46, v176
	v_add_f32_e32 v47, v47, v177
	ds_read_b32 v162, v183 offset:108
	ds_read_b32 v163, v183 offset:104
	ds_read_b32 v164, v183 offset:100
	ds_read_b32 v165, v183 offset:96
	ds_read_b32 v166, v183 offset:76
	ds_read_b32 v167, v183 offset:72
	ds_read_b32 v168, v183 offset:68
	ds_read_b32 v169, v183 offset:64
	ds_read_b32 v170, v183 offset:44
	ds_read_b32 v171, v183 offset:40
	ds_read_b32 v172, v183 offset:36
	ds_read_b32 v173, v183 offset:32
	ds_read_b32 v174, v183 offset:12
	ds_read_b32 v175, v183 offset:8
	ds_read_b32 v176, v183 offset:4
	ds_read_b32 v177, v183 offset:0
	s_waitcnt lgkmcnt(8)
	v_add_f32_e32 v48, v48, v162
	v_add_f32_e32 v49, v49, v163
	v_add_f32_e32 v50, v50, v164
	v_add_f32_e32 v51, v51, v165
	v_add_f32_e32 v52, v52, v166
	v_add_f32_e32 v53, v53, v167
	v_add_f32_e32 v54, v54, v168
	v_add_f32_e32 v55, v55, v169
	s_waitcnt lgkmcnt(0)
	v_add_f32_e32 v56, v56, v170
	v_add_f32_e32 v57, v57, v171
	v_add_f32_e32 v58, v58, v172
	v_add_f32_e32 v59, v59, v173
	v_add_f32_e32 v60, v60, v174
	v_add_f32_e32 v61, v61, v175
	v_add_f32_e32 v62, v62, v176
	v_add_f32_e32 v63, v63, v177
	s_cmp_ge_i32 s61, 2
	s_cbranch_scc1 .Lamoba_softmax
; #define NEGINF (-__builtin_inff())
; DI int crow(int i, int h) { return (i & 3) + 8 * (i >> 2) + 4 * h; }
; DI void moba_item(const Params& p, int b, int hd, int qb, const unsigned char* blut, const float* tbl) {
;     ...
;         int dist[16]; float bv[16];
; #pragma unroll
;         for (int i = 0; i < 16; ++i) dist[i] = t - (kt * 32 + crow(i, h));
;         bias16(blut, tblh, dist, bv);
; #pragma unroll
;         for (int i = 0; i < 16; ++i) lg[i] = (bs && dist[i] >= 0) ? s[i] + bv[i] : NEGINF;
	v_subrev_u32_e32 v184, 32, v179
	v_cmp_le_i32_e32 vcc, 0, v179
	s_nop 1
	v_cndmask_b32_e32 v32, v199, v32, vcc
	v_cmp_le_i32_e32 vcc, 1, v179
	s_nop 1
	v_cndmask_b32_e32 v33, v199, v33, vcc
	v_cmp_le_i32_e32 vcc, 2, v179
	s_nop 1
	v_cndmask_b32_e32 v34, v199, v34, vcc
	v_cmp_le_i32_e32 vcc, 3, v179
	s_nop 1
	v_cndmask_b32_e32 v35, v199, v35, vcc
	v_cmp_le_i32_e32 vcc, 8, v179
	s_nop 1
	v_cndmask_b32_e32 v36, v199, v36, vcc
	v_cmp_le_i32_e32 vcc, 9, v179
	s_nop 1
	v_cndmask_b32_e32 v37, v199, v37, vcc
	v_cmp_le_i32_e32 vcc, 10, v179
	s_nop 1
	v_cndmask_b32_e32 v38, v199, v38, vcc
	v_cmp_le_i32_e32 vcc, 11, v179
	s_nop 1
	v_cndmask_b32_e32 v39, v199, v39, vcc
	v_cmp_le_i32_e32 vcc, 16, v179
	s_nop 1
	v_cndmask_b32_e32 v40, v199, v40, vcc
	v_cmp_le_i32_e32 vcc, 17, v179
	s_nop 1
	v_cndmask_b32_e32 v41, v199, v41, vcc
	v_cmp_le_i32_e32 vcc, 18, v179
	s_nop 1
	v_cndmask_b32_e32 v42, v199, v42, vcc
	v_cmp_le_i32_e32 vcc, 19, v179
	s_nop 1
	v_cndmask_b32_e32 v43, v199, v43, vcc
	v_cmp_le_i32_e32 vcc, 24, v179
	s_nop 1
	v_cndmask_b32_e32 v44, v199, v44, vcc
	v_cmp_le_i32_e32 vcc, 25, v179
	s_nop 1
	v_cndmask_b32_e32 v45, v199, v45, vcc
	v_cmp_le_i32_e32 vcc, 26, v179
	s_nop 1
	v_cndmask_b32_e32 v46, v199, v46, vcc
	v_cmp_le_i32_e32 vcc, 27, v179
	s_nop 1
	v_cndmask_b32_e32 v47, v199, v47, vcc
	v_cmp_le_i32_e32 vcc, 0, v184
	s_nop 1
	v_cndmask_b32_e32 v48, v199, v48, vcc
	v_cmp_le_i32_e32 vcc, 1, v184
	s_nop 1
	v_cndmask_b32_e32 v49, v199, v49, vcc
	v_cmp_le_i32_e32 vcc, 2, v184
	s_nop 1
	v_cndmask_b32_e32 v50, v199, v50, vcc
	v_cmp_le_i32_e32 vcc, 3, v184
	s_nop 1
	v_cndmask_b32_e32 v51, v199, v51, vcc
	v_cmp_le_i32_e32 vcc, 8, v184
	s_nop 1
	v_cndmask_b32_e32 v52, v199, v52, vcc
	v_cmp_le_i32_e32 vcc, 9, v184
	s_nop 1
	v_cndmask_b32_e32 v53, v199, v53, vcc
	v_cmp_le_i32_e32 vcc, 10, v184
	s_nop 1
	v_cndmask_b32_e32 v54, v199, v54, vcc
	v_cmp_le_i32_e32 vcc, 11, v184
	s_nop 1
	v_cndmask_b32_e32 v55, v199, v55, vcc
	v_cmp_le_i32_e32 vcc, 16, v184
	s_nop 1
	v_cndmask_b32_e32 v56, v199, v56, vcc
	v_cmp_le_i32_e32 vcc, 17, v184
	s_nop 1
	v_cndmask_b32_e32 v57, v199, v57, vcc
	v_cmp_le_i32_e32 vcc, 18, v184
	s_nop 1
	v_cndmask_b32_e32 v58, v199, v58, vcc
	v_cmp_le_i32_e32 vcc, 19, v184
	s_nop 1
	v_cndmask_b32_e32 v59, v199, v59, vcc
	v_cmp_le_i32_e32 vcc, 24, v184
	s_nop 1
	v_cndmask_b32_e32 v60, v199, v60, vcc
	v_cmp_le_i32_e32 vcc, 25, v184
	s_nop 1
	v_cndmask_b32_e32 v61, v199, v61, vcc
	v_cmp_le_i32_e32 vcc, 26, v184
	s_nop 1
	v_cndmask_b32_e32 v62, v199, v62, vcc
	v_cmp_le_i32_e32 vcc, 27, v184
	s_nop 1
	v_cndmask_b32_e32 v63, v199, v63, vcc
	s_branch .Lamoba_softmax

; #define MFMA32(a, b, c) __builtin_amdgcn_mfma_f32_32x32x16_bf16((a), (b), (c), 0, 0, 0)
; #define NEGINF (-__builtin_inff())
; DI int crow(int i, int h) { return (i & 3) + 8 * (i >> 2) + 4 * h; }
; template <class KP, class VP, class ACT, class FILL>
; DI void attn_loop(AttnSt& st, const bf16x8 (&qf)[4], int k0, int k1, size_t vstride, KP kp, VP vp, ACT act, FILL fill) {
;     ...
;   for (int kt = k0; kt <= k1; ++kt) {
;     const int kn = (kt < k1) ? kt + 1 : k1;
;     const int kn2 = (kt + 2 <= k1) ? kt + 2 : k1;
;     {
;       const bf16_t* v0 = vp(kn);
; #pragma unroll
;       for (int j = 0; j < 8; ++j) nxt.v[j] = *(const s16x4*)(v0 + 256 * j);
;     }
;     bf16x8 k2[4];
;     {
;       const bf16_t* krow = kp(kn2);
; #pragma unroll
;       for (int ss = 0; ss < 4; ++ss) k2[ss] = *(const bf16x8*)(krow + 512 * ss);
;     }
;     f32x16 s_next;
; #pragma unroll
;     for (int i = 0; i < 16; ++i) s_next[i] = 0.f;
; #pragma unroll
;     for (int ss = 0; ss < 4; ++ss) s_next = MFMA32(nxt.k[ss], qf[ss], s_next);
; DI void nsa_win_item(const Params& p, int b, int head, int qb, const unsigned char* blut, const float* tbl) {
;     ...
;     attn_loop(st, qf, k0, qb, 32,
;       [&](int kt) { return K + (size_t)kt * 2048 + (h * 32 + r) * 8; },
;       [&](int kt) { return Vt + (size_t)kt * 2048 + (h * 32 + r) * 4; },
;       [&](int kt) { return true; },
;       [&](int kt, const f32x16& s, float (&lg)[16]) {
;         int dist[16]; float bv[16];
; #pragma unroll
;         for (int i = 0; i < 16; ++i) dist[i] = t - (kt * 32 + crow(i, h));
;         bias16(blut, tblh, dist, bv);
; #pragma unroll
;         for (int i = 0; i < 16; ++i) lg[i] = (dist[i] >= 0 && dist[i] < 512) ? s[i] + bv[i] : NEGINF;
;       });
.Lawin4_loop:
	s_waitcnt vmcnt(2)
	s_barrier
	s_lshr_b32 s23, s56, 1
	s_add_u32 s23, s23, 2
	s_sub_u32 s61, s64, 0x4000
	s_cmp_lt_u32 s61, 0x10000
	s_cselect_b32 s61, 0x18000, s61
	s_lshr_b32 s24, s59, 1
	s_min_u32 s24, s23, s24
	s_lshl_b32 s26, s24, 13
	s_lshl_b32 s24, s58, 10
	s_add_u32 s26, s26, s24
	s_mov_b32 s27, 0
	v_lshl_add_u64 v[186:187], v[116:117], 0, s[26:27]
	v_lshl_add_u64 v[126:127], v[114:115], 0, s[26:27]
	v_add_co_u32_e32 v126, vcc, v126, v185
	v_addc_co_u32_e32 v127, vcc, 0, v127, vcc
	s_add_u32 s24, s24, s61
	s_mov_b32 m0, s24
	s_nop 0
	global_load_lds_dwordx4 v[186:187], off
	s_add_u32 s24, s24, 0x2000
	s_mov_b32 m0, s24
	s_nop 0
	global_load_lds_dwordx4 v[126:127], off
	s_cmp_le_u32 s56, s60
	s_cbranch_scc0 .Lawin4_skip
	s_add_u32 s24, s56, 1
	s_cmp_ge_u32 s24, s65
	s_cbranch_scc0 .Lawin4_skip
	v_lshl_add_u32 v186, v185, 1, s64
	ds_read_b128 v[80:83], v186 offset:0
	ds_read_b128 v[96:99], v186 offset:4096
	ds_read_b128 v[84:87], v186 offset:1024
	ds_read_b128 v[100:103], v186 offset:5120
	ds_read_b128 v[88:91], v186 offset:2048
	ds_read_b128 v[104:107], v186 offset:6144
	ds_read_b128 v[92:95], v186 offset:3072
	ds_read_b128 v[108:111], v186 offset:7168
	s_sub_i32 s61, s60, s56
	s_waitcnt lgkmcnt(6)
	v_mfma_f32_32x32x16_bf16 v[32:47], v[80:83], v[64:67], 0
	v_mfma_f32_32x32x16_bf16 v[48:63], v[96:99], v[64:67], 0
	s_waitcnt lgkmcnt(4)
	v_mfma_f32_32x32x16_bf16 v[32:47], v[84:87], v[68:71], v[32:47]
	v_mfma_f32_32x32x16_bf16 v[48:63], v[100:103], v[68:71], v[48:63]
	s_waitcnt lgkmcnt(2)
	v_mfma_f32_32x32x16_bf16 v[32:47], v[88:91], v[72:75], v[32:47]
	v_mfma_f32_32x32x16_bf16 v[48:63], v[104:107], v[72:75], v[48:63]
	s_waitcnt lgkmcnt(0)
	v_mfma_f32_32x32x16_bf16 v[32:47], v[92:95], v[76:79], v[32:47]
	v_mfma_f32_32x32x16_bf16 v[48:63], v[108:111], v[76:79], v[48:63]
	v_add_u32_e32 v126, s64, v185
	ds_read_b64 v[146:147], v126 offset:8192
	ds_read_b64 v[148:149], v126 offset:8704
	ds_read_b64 v[150:151], v126 offset:9216
	ds_read_b64 v[152:153], v126 offset:9728
	ds_read_b64 v[154:155], v126 offset:10240
	ds_read_b64 v[156:157], v126 offset:10752
	ds_read_b64 v[158:159], v126 offset:11264
	ds_read_b64 v[160:161], v126 offset:11776
	ds_read_b64 v[162:163], v126 offset:12288
	ds_read_b64 v[164:165], v126 offset:12800
	ds_read_b64 v[166:167], v126 offset:13312
	ds_read_b64 v[168:169], v126 offset:13824
	ds_read_b64 v[170:171], v126 offset:14336
	ds_read_b64 v[172:173], v126 offset:14848
	ds_read_b64 v[174:175], v126 offset:15360
	ds_read_b64 v[176:177], v126 offset:15872
	s_cmp_ge_i32 s61, 50
	s_cbranch_scc1 .Lawin4_far
	s_lshl_b32 s23, s61, 5
	v_add_u32_e32 v179, s23, v142
	v_lshl_add_u32 v182, v179, 2, v180
	v_subrev_u32_e32 v183, 128, v182
	ds_read_b32 v118, v182 offset:108
	ds_read_b32 v119, v182 offset:104
	ds_read_b32 v120, v182 offset:100
	ds_read_b32 v121, v182 offset:96
	ds_read_b32 v122, v182 offset:76
	ds_read_b32 v123, v182 offset:72
	ds_read_b32 v124, v182 offset:68
	ds_read_b32 v125, v182 offset:64
	ds_read_b32 v132, v182 offset:44
	ds_read_b32 v133, v182 offset:40
	ds_read_b32 v134, v182 offset:36
	ds_read_b32 v135, v182 offset:32
	ds_read_b32 v218, v182 offset:12
	ds_read_b32 v219, v182 offset:8
	ds_read_b32 v220, v182 offset:4
	ds_read_b32 v221, v182 offset:0
	s_waitcnt lgkmcnt(8)
	v_add_f32_e32 v32, v32, v118
	v_add_f32_e32 v33, v33, v119
	v_add_f32_e32 v34, v34, v120
	v_add_f32_e32 v35, v35, v121
	v_add_f32_e32 v36, v36, v122
	v_add_f32_e32 v37, v37, v123
	v_add_f32_e32 v38, v38, v124
	v_add_f32_e32 v39, v39, v125
	s_waitcnt lgkmcnt(0)
	v_add_f32_e32 v40, v40, v132
	v_add_f32_e32 v41, v41, v133
	v_add_f32_e32 v42, v42, v134
	v_add_f32_e32 v43, v43, v135
	v_add_f32_e32 v44, v44, v218
	v_add_f32_e32 v45, v45, v219
	v_add_f32_e32 v46, v46, v220
	v_add_f32_e32 v47, v47, v221
	ds_read_b32 v118, v183 offset:108
	ds_read_b32 v119, v183 offset:104
	ds_read_b32 v120, v183 offset:100
	ds_read_b32 v121, v183 offset:96
	ds_read_b32 v122, v183 offset:76
	ds_read_b32 v123, v183 offset:72
	ds_read_b32 v124, v183 offset:68
	ds_read_b32 v125, v183 offset:64
	ds_read_b32 v132, v183 offset:44
	ds_read_b32 v133, v183 offset:40
	ds_read_b32 v134, v183 offset:36
	ds_read_b32 v135, v183 offset:32
	ds_read_b32 v218, v183 offset:12
	ds_read_b32 v219, v183 offset:8
	ds_read_b32 v220, v183 offset:4
	ds_read_b32 v221, v183 offset:0
	s_waitcnt lgkmcnt(8)
	v_add_f32_e32 v48, v48, v118
	v_add_f32_e32 v49, v49, v119
	v_add_f32_e32 v50, v50, v120
	v_add_f32_e32 v51, v51, v121
	v_add_f32_e32 v52, v52, v122
	v_add_f32_e32 v53, v53, v123
	v_add_f32_e32 v54, v54, v124
	v_add_f32_e32 v55, v55, v125
	s_waitcnt lgkmcnt(0)
	v_add_f32_e32 v56, v56, v132
	v_add_f32_e32 v57, v57, v133
	v_add_f32_e32 v58, v58, v134
	v_add_f32_e32 v59, v59, v135
	v_add_f32_e32 v60, v60, v218
	v_add_f32_e32 v61, v61, v219
	v_add_f32_e32 v62, v62, v220
	v_add_f32_e32 v63, v63, v221
	s_cmp_ge_i32 s61, 15
	s_cbranch_scc0 .Lawin4_nowin
; #define NEGINF (-__builtin_inff())
; DI int crow(int i, int h) { return (i & 3) + 8 * (i >> 2) + 4 * h; }
; DI void nsa_win_item(const Params& p, int b, int head, int qb, const unsigned char* blut, const float* tbl) {
;     ...
;       [&](int kt, const f32x16& s, float (&lg)[16]) {
;         int dist[16]; float bv[16];
; #pragma unroll
;         for (int i = 0; i < 16; ++i) dist[i] = t - (kt * 32 + crow(i, h));
;         bias16(blut, tblh, dist, bv);
; #pragma unroll
;         for (int i = 0; i < 16; ++i) lg[i] = (dist[i] >= 0 && dist[i] < 512) ? s[i] + bv[i] : NEGINF;
;       });
	v_subrev_u32_e32 v184, 32, v179
	v_cmp_gt_i32_e32 vcc, 0x200, v179
	s_nop 1
	v_cndmask_b32_e32 v32, v199, v32, vcc
	v_cmp_gt_i32_e32 vcc, 0x201, v179
	s_nop 1
	v_cndmask_b32_e32 v33, v199, v33, vcc
	v_cmp_gt_i32_e32 vcc, 0x202, v179
	s_nop 1
	v_cndmask_b32_e32 v34, v199, v34, vcc
	v_cmp_gt_i32_e32 vcc, 0x203, v179
	s_nop 1
	v_cndmask_b32_e32 v35, v199, v35, vcc
	v_cmp_gt_i32_e32 vcc, 0x208, v179
	s_nop 1
	v_cndmask_b32_e32 v36, v199, v36, vcc
	v_cmp_gt_i32_e32 vcc, 0x209, v179
	s_nop 1
	v_cndmask_b32_e32 v37, v199, v37, vcc
	v_cmp_gt_i32_e32 vcc, 0x20a, v179
	s_nop 1
	v_cndmask_b32_e32 v38, v199, v38, vcc
	v_cmp_gt_i32_e32 vcc, 0x20b, v179
	s_nop 1
	v_cndmask_b32_e32 v39, v199, v39, vcc
	v_cmp_gt_i32_e32 vcc, 0x210, v179
	s_nop 1
	v_cndmask_b32_e32 v40, v199, v40, vcc
	v_cmp_gt_i32_e32 vcc, 0x211, v179
	s_nop 1
	v_cndmask_b32_e32 v41, v199, v41, vcc
	v_cmp_gt_i32_e32 vcc, 0x212, v179
	s_nop 1
	v_cndmask_b32_e32 v42, v199, v42, vcc
	v_cmp_gt_i32_e32 vcc, 0x213, v179
	s_nop 1
	v_cndmask_b32_e32 v43, v199, v43, vcc
	v_cmp_gt_i32_e32 vcc, 0x218, v179
	s_nop 1
	v_cndmask_b32_e32 v44, v199, v44, vcc
	v_cmp_gt_i32_e32 vcc, 0x219, v179
	s_nop 1
	v_cndmask_b32_e32 v45, v199, v45, vcc
	v_cmp_gt_i32_e32 vcc, 0x21a, v179
	s_nop 1
	v_cndmask_b32_e32 v46, v199, v46, vcc
	v_cmp_gt_i32_e32 vcc, 0x21b, v179
	s_nop 1
	v_cndmask_b32_e32 v47, v199, v47, vcc
	v_cmp_gt_i32_e32 vcc, 0x200, v184
	s_nop 1
	v_cndmask_b32_e32 v48, v199, v48, vcc
	v_cmp_gt_i32_e32 vcc, 0x201, v184
	s_nop 1
	v_cndmask_b32_e32 v49, v199, v49, vcc
	v_cmp_gt_i32_e32 vcc, 0x202, v184
	s_nop 1
	v_cndmask_b32_e32 v50, v199, v50, vcc
	v_cmp_gt_i32_e32 vcc, 0x203, v184
	s_nop 1
	v_cndmask_b32_e32 v51, v199, v51, vcc
	v_cmp_gt_i32_e32 vcc, 0x208, v184
	s_nop 1
	v_cndmask_b32_e32 v52, v199, v52, vcc
	v_cmp_gt_i32_e32 vcc, 0x209, v184
	s_nop 1
	v_cndmask_b32_e32 v53, v199, v53, vcc
	v_cmp_gt_i32_e32 vcc, 0x20a, v184
	s_nop 1
	v_cndmask_b32_e32 v54, v199, v54, vcc
	v_cmp_gt_i32_e32 vcc, 0x20b, v184
	s_nop 1
	v_cndmask_b32_e32 v55, v199, v55, vcc
	v_cmp_gt_i32_e32 vcc, 0x210, v184
	s_nop 1
	v_cndmask_b32_e32 v56, v199, v56, vcc
	v_cmp_gt_i32_e32 vcc, 0x211, v184
	s_nop 1
	v_cndmask_b32_e32 v57, v199, v57, vcc
	v_cmp_gt_i32_e32 vcc, 0x212, v184
	s_nop 1
	v_cndmask_b32_e32 v58, v199, v58, vcc
	v_cmp_gt_i32_e32 vcc, 0x213, v184
	s_nop 1
	v_cndmask_b32_e32 v59, v199, v59, vcc
	v_cmp_gt_i32_e32 vcc, 0x218, v184
	s_nop 1
	v_cndmask_b32_e32 v60, v199, v60, vcc
	v_cmp_gt_i32_e32 vcc, 0x219, v184
	s_nop 1
	v_cndmask_b32_e32 v61, v199, v61, vcc
	v_cmp_gt_i32_e32 vcc, 0x21a, v184
	s_nop 1
	v_cndmask_b32_e32 v62, v199, v62, vcc
	v_cmp_gt_i32_e32 vcc, 0x21b, v184
	s_nop 1
	v_cndmask_b32_e32 v63, v199, v63, vcc
